# v36 with the whole instruction stream shifted by 4 bytes (one s_nop 0 at entry): code-placement phase test of the hot loops
# baseline (speedup 1.0000x reference)
; #define LAS __attribute__((address_space(3)))
; __device__ __forceinline__ unsigned xb_add(unsigned* p, unsigned v) { return __hip_atomic_fetch_add(p, v, __ATOMIC_RELAXED, __HIP_MEMORY_SCOPE_AGENT); }
; __device__ __forceinline__ unsigned xb_xcc_id() { return (unsigned)__builtin_amdgcn_s_getreg((3 << 11) | 20) & 0xFu; }
; __device__ __forceinline__ XcdBarrier xcd_barrier_post(unsigned* bar, volatile LAS unsigned* st) {
;     XcdBarrier b; b.bar = bar; b.x = xb_xcc_id(); b.st = st;
;     if (threadIdx.x == 0) (void)xb_add(&bar[XB_XCNT(b.x)], 1u);
;     return b;
; __global__ void __launch_bounds__(512) fwd_megakernel(Args a) {
;     extern __shared__ __attribute__((aligned(16))) unsigned char lds_raw[];
;     LAS unsigned char* lds = (LAS unsigned char*)lds_raw;
;     cg::grid_group grid = cg::this_grid();
;     ...
;     { volatile LAS unsigned* st0 = (volatile LAS unsigned*)(lds + 147456 - 64); if (threadIdx.x < 16) st0[threadIdx.x] = 0u; }
;     __syncthreads();
;     const XcdBarrier xbar = xcd_barrier_post((unsigned*)(a.ws + WS_BAR), (volatile LAS unsigned*)(lds + 147456 - 64));
_Z14fwd_megakernel4Args:
	s_nop 0
	s_load_dwordx8 s[4:11], s[0:1], 0xc0
	v_and_b32_e32 v1, 0x3ff, v0
	s_mov_b32 s34, s2
	v_cmp_gt_u32_e32 vcc, 16, v1
	s_waitcnt lgkmcnt(0)
	v_writelane_b32 v250, s4, 0
	s_nop 1
	v_writelane_b32 v250, s5, 1
	v_writelane_b32 v250, s6, 2
	v_writelane_b32 v250, s7, 3
	v_writelane_b32 v250, s8, 4
	v_writelane_b32 v250, s9, 5
	v_writelane_b32 v250, s10, 6
	v_writelane_b32 v250, s11, 7
	s_load_dword s93, s[0:1], 0xf8
	s_load_dwordx4 s[4:7], s[0:1], 0xe0
	s_load_dwordx2 s[30:31], s[0:1], 0xf0
	s_waitcnt lgkmcnt(0)
	v_writelane_b32 v250, s4, 8
	s_nop 1
	v_writelane_b32 v250, s5, 9
	v_writelane_b32 v250, s6, 10
	v_writelane_b32 v250, s7, 11
	s_add_u32 s4, s0, 0xf0
	s_addc_u32 s5, s1, 0
	v_writelane_b32 v250, s4, 12
	s_nop 1
	v_writelane_b32 v250, s5, 13
	s_and_saveexec_b64 s[4:5], vcc
	v_lshl_add_u32 v2, v1, 2, 0
	v_add_u32_e32 v2, 0x23fc0, v2
	v_mov_b32_e32 v3, 0
	ds_write_b32 v2, v3
	s_or_b64 exec, exec, s[4:5]
	s_load_dwordx4 s[4:7], s[0:1], 0xe0
	s_waitcnt lgkmcnt(0)
	s_barrier
	s_getreg_b32 s3, hwreg(HW_REG_XCC_ID, 0, 4)
	s_add_u32 s8, s6, 0x780000
	s_addc_u32 s9, s7, 0
	s_and_b32 s20, s3, 15
	v_cmp_eq_u32_e64 s[2:3], 0, v1
	s_nop 1
	v_writelane_b32 v250, s2, 14
	s_nop 1
	v_writelane_b32 v250, s3, 15
	s_and_saveexec_b64 s[4:5], s[2:3]
	s_cbranch_execz .LBB0_5
	s_mov_b64 s[6:7], exec
	v_mbcnt_lo_u32_b32 v2, s6, 0
	v_mbcnt_hi_u32_b32 v2, s7, v2
	v_cmp_eq_u32_e32 vcc, 0, v2
	s_and_b64 s[10:11], exec, vcc
	s_mov_b64 exec, s[10:11]
	s_cbranch_execz .LBB0_5
	s_lshl_b32 s3, s20, 8
	s_bcnt1_i32_b64 s6, s[6:7]
	v_mov_b32_e32 v2, s3
	v_mov_b32_e32 v3, s6
	global_atomic_add v2, v3, s[8:9] offset:1024
